# mixer-B HB row loads with sc1 (L1 bypass)
# speedup vs baseline: 1.0066x; 1.0066x over previous
.LBB0_314:
	s_or_b64 exec, exec, s[40:41]
	v_or_b32_e32 v187, s11, v233
	v_lshlrev_b32_e32 v187, 11, v187
	v_lshl_add_u32 v187, v210, 1, v187
	v_mov_b32_e32 v250, 0
	v_mov_b32_e32 v251, 0
	v_mov_b32_e32 v252, 0
	v_mov_b32_e32 v253, 0
	s_mov_b64 s[40:41], exec
	s_and_b64 exec, exec, s[8:9]
	v_add_u32_e32 v187, 0x38000, v187
	s_nop 0
	global_load_dwordx4 v[250:253], v187, s[50:51]
	v_add_u32_e32 v187, 0xfffc8000, v187
	s_mov_b64 exec, s[40:41]
	global_load_dwordx4 v[188:191], v187, s[50:51] sc1
	v_add_u32_e32 v187, 0x8000, v187
	global_load_dwordx4 v[192:195], v187, s[50:51] sc1
	v_add_u32_e32 v187, 0x8000, v187
	global_load_dwordx4 v[196:199], v187, s[50:51] sc1
	v_add_u32_e32 v187, 0x8000, v187
	global_load_dwordx4 v[228:231], v187, s[50:51] sc1
	v_add_u32_e32 v187, 0x28000, v187
	global_load_dwordx4 v[246:249], v187, s[50:51] sc1
	v_mul_f32_e32 v144, 0xbfb8aa3b, v128
	v_mul_f32_e32 v145, 0xbfb8aa3b, v129
	v_exp_f32_e32 v144, v144
	v_exp_f32_e32 v145, v145
	v_mul_f32_e32 v146, 0xbfb8aa3b, v130
	v_mul_f32_e32 v147, 0xbfb8aa3b, v131
	v_exp_f32_e32 v146, v146
	v_exp_f32_e32 v147, v147
	v_add_f32_e32 v144, 1.0, v144
	v_add_f32_e32 v145, 1.0, v145
	v_rcp_f32_e32 v144, v144
	v_rcp_f32_e32 v145, v145
	v_add_f32_e32 v146, 1.0, v146
	v_add_f32_e32 v147, 1.0, v147
	v_rcp_f32_e32 v146, v146
	v_rcp_f32_e32 v147, v147
	v_pk_mul_f32 v[164:165], v[128:129], v[144:145]
	v_mul_f32_e32 v144, 0xbfb8aa3b, v120
	v_mul_f32_e32 v145, 0xbfb8aa3b, v121
	v_exp_f32_e32 v144, v144
	v_exp_f32_e32 v145, v145
	v_pk_mul_f32 v[166:167], v[130:131], v[146:147]
	v_mul_f32_e32 v146, 0xbfb8aa3b, v122
	v_mul_f32_e32 v147, 0xbfb8aa3b, v123
	v_exp_f32_e32 v146, v146
	v_exp_f32_e32 v147, v147
	v_add_f32_e32 v144, 1.0, v144
	v_add_f32_e32 v145, 1.0, v145
	v_rcp_f32_e32 v144, v144
	v_rcp_f32_e32 v145, v145
	v_or_b32_e32 v162, s11, v233
	v_add_f32_e32 v146, 1.0, v146
	v_add_f32_e32 v147, 1.0, v147
	v_rcp_f32_e32 v146, v146
	v_rcp_f32_e32 v147, v147
	v_ashrrev_i32_e32 v163, 31, v162
	v_pk_mul_f32 v[170:171], v[120:121], v[144:145]
	v_lshlrev_b64 v[144:145], 11, v[162:163]
	v_lshl_add_u64 v[144:145], s[50:51], 0, v[144:145]
	v_lshlrev_b64 v[160:161], 1, v[210:211]
	v_lshl_add_u64 v[144:145], v[144:145], 0, v[160:161]
	v_pk_mul_f32 v[168:169], v[122:123], v[146:147]
	s_waitcnt vmcnt(4)
	v_mov_b32_e32 v144, v188
	v_mov_b32_e32 v145, v189
	v_mov_b32_e32 v146, v190
	v_mov_b32_e32 v147, v191
	v_add_u32_e32 v187, 0x8000, v187
	global_load_dwordx4 v[188:191], v187, s[50:51] sc1
	v_mov_b32_e32 v173, v211
	v_mov_b32_e32 v174, v211
	v_mov_b32_e32 v175, v211
	v_mov_b32_e32 v176, v211
	v_mov_b32_e32 v177, v211
	v_mov_b32_e32 v178, v211
	v_mov_b32_e32 v179, v211
	v_pk_mul_f32 v[170:171], v[124:125], v[170:171]
	v_pk_mul_f32 v[168:169], v[126:127], v[168:169]
	v_mov_b32_e32 v184, v211
	v_mov_b32_e32 v185, v211
	s_movk_i32 s16, 0x7ff
	v_cndmask_b32_e64 v172, v144, v156, s[4:5]
	v_cndmask_b32_e64 v156, v156, v144, s[0:1]
	s_nop 0
	v_mov_b32_dpp v173, v172 row_ror:1 row_mask:0xf bank_mask:0xf
	v_mov_b32_e32 v172, v211
	s_nop 1
	v_mov_b32_dpp v172, v156 row_ror:2 row_mask:0xf bank_mask:0xf
	v_cndmask_b32_e64 v156, v145, v157, s[4:5]
	v_cndmask_b32_e64 v157, v157, v145, s[0:1]
	v_lshlrev_b32_e32 v180, 16, v172
	v_mov_b32_dpp v174, v156 row_ror:1 row_mask:0xf bank_mask:0xf
	v_mov_b32_dpp v175, v157 row_ror:2 row_mask:0xf bank_mask:0xf
	v_cndmask_b32_e64 v156, v146, v158, s[4:5]
	v_cndmask_b32_e64 v157, v158, v146, s[0:1]
	v_lshlrev_b32_e32 v158, 16, v144
	v_mov_b32_dpp v176, v156 row_ror:1 row_mask:0xf bank_mask:0xf
	v_mov_b32_dpp v177, v157 row_ror:2 row_mask:0xf bank_mask:0xf
	v_cndmask_b32_e64 v156, v147, v159, s[4:5]
	v_cndmask_b32_e64 v157, v159, v147, s[0:1]
	v_lshlrev_b32_e32 v159, 16, v173
	v_mov_b32_dpp v178, v156 row_ror:1 row_mask:0xf bank_mask:0xf
	v_mov_b32_dpp v179, v157 row_ror:2 row_mask:0xf bank_mask:0xf
	v_mov_b32_e32 v156, v152
	v_mov_b32_e32 v157, v140
	v_pk_mul_f32 v[158:159], v[156:157], v[158:159]
	v_and_b32_e32 v172, 0xffff0000, v172
	v_fma_f32 v140, v136, v180, v159
	v_add_f32_e32 v180, v158, v140
	v_and_b32_e32 v159, 0xffff0000, v173
	v_and_b32_e32 v158, 0xffff0000, v144
	v_mov_b32_e32 v140, v153
	v_pk_mul_f32 v[152:153], v[140:141], v[158:159]
	v_lshlrev_b32_e32 v158, 16, v145
	v_fma_f32 v153, v137, v172, v153
	v_add_f32_e32 v172, v152, v153
	v_lshlrev_b32_e32 v159, 16, v174
	v_mov_b32_e32 v152, v154
	v_mov_b32_e32 v153, v142
	v_lshlrev_b32_e32 v173, 16, v175
	v_pk_mul_f32 v[158:159], v[152:153], v[158:159]
	v_and_b32_e32 v175, 0xffff0000, v175
	v_fma_f32 v142, v138, v173, v159
	v_add_f32_e32 v173, v158, v142
	v_and_b32_e32 v159, 0xffff0000, v174
	v_and_b32_e32 v158, 0xffff0000, v145
	v_mov_b32_e32 v142, v155
	v_pk_mul_f32 v[154:155], v[142:143], v[158:159]
	v_lshlrev_b32_e32 v158, 16, v146
	v_fma_f32 v155, v139, v175, v155
	v_add_f32_e32 v174, v154, v155
	v_lshlrev_b32_e32 v159, 16, v176
	v_mov_b32_e32 v154, v148
	v_mov_b32_e32 v155, v116
	v_lshlrev_b32_e32 v175, 16, v177
	v_pk_mul_f32 v[158:159], v[154:155], v[158:159]
	v_and_b32_e32 v177, 0xffff0000, v177
	v_fma_f32 v116, v112, v175, v159
	v_add_f32_e32 v175, v158, v116
	v_and_b32_e32 v159, 0xffff0000, v176
	v_and_b32_e32 v158, 0xffff0000, v146
	v_mov_b32_e32 v116, v149
	v_pk_mul_f32 v[148:149], v[116:117], v[158:159]
	v_mov_b32_e32 v158, v150
	v_fma_f32 v149, v113, v177, v149
	v_add_f32_e32 v176, v148, v149
	v_lshlrev_b32_e32 v148, 16, v147
	v_lshlrev_b32_e32 v149, 16, v178
	v_mov_b32_e32 v159, v118
	v_lshlrev_b32_e32 v177, 16, v179
	v_pk_mul_f32 v[148:149], v[158:159], v[148:149]
	v_and_b32_e32 v150, 0xffff0000, v179
	v_fma_f32 v118, v114, v177, v149
	v_add_f32_e32 v177, v148, v118
	v_and_b32_e32 v149, 0xffff0000, v178
	v_and_b32_e32 v148, 0xffff0000, v147
	v_mov_b32_e32 v118, v151
	v_pk_mul_f32 v[148:149], v[118:119], v[148:149]
	v_mov_b32_e32 v179, v211
	v_fma_f32 v149, v115, v150, v149
	v_add_f32_e32 v178, v148, v149
	v_pk_mul_f32 v[148:149], v[132:133], v[164:165]
	v_pk_mul_f32 v[150:151], v[134:135], v[166:167]
	v_mul_f32_e32 v148, v148, v180
	v_mul_f32_e32 v149, v149, v172
	v_cvt_pk_bf16_f32 v148, v148, v149
	v_mul_f32_e32 v149, v150, v173
	v_mul_f32_e32 v150, v151, v174
	v_cvt_pk_bf16_f32 v149, v149, v150
	v_mul_f32_e32 v150, v170, v175
	v_mul_f32_e32 v151, v171, v176
	v_cvt_pk_bf16_f32 v150, v150, v151
	v_mul_f32_e32 v151, v168, v177
	v_mul_f32_e32 v164, v169, v178
	v_cvt_pk_bf16_f32 v151, v151, v164
	v_lshlrev_b64 v[164:165], 12, v[162:163]
	v_lshl_add_u64 v[164:165], s[12:13], 0, v[164:165]
	v_lshl_add_u64 v[164:165], v[164:165], 0, v[160:161]
	global_store_dwordx4 v[164:165], v[148:151], off offset:2048 sc1
	v_or_b32_e32 v172, 16, v162
	v_ashrrev_i32_e32 v173, 31, v172
	v_mul_f32_e32 v148, 0xbfb8aa3b, v104
	v_mul_f32_e32 v149, 0xbfb8aa3b, v105
	v_exp_f32_e32 v148, v148
	v_exp_f32_e32 v149, v149
	v_mul_f32_e32 v150, 0xbfb8aa3b, v106
	v_mul_f32_e32 v151, 0xbfb8aa3b, v107
	v_exp_f32_e32 v150, v150
	v_exp_f32_e32 v151, v151
	v_add_f32_e32 v148, 1.0, v148
	v_add_f32_e32 v149, 1.0, v149
	v_rcp_f32_e32 v148, v148
	v_rcp_f32_e32 v149, v149
	v_add_f32_e32 v150, 1.0, v150
	v_add_f32_e32 v151, 1.0, v151
	v_rcp_f32_e32 v150, v150
	v_rcp_f32_e32 v151, v151
	v_pk_mul_f32 v[164:165], v[104:105], v[148:149]
	v_mul_f32_e32 v148, 0xbfb8aa3b, v96
	v_mul_f32_e32 v149, 0xbfb8aa3b, v97
	v_exp_f32_e32 v148, v148
	v_exp_f32_e32 v149, v149
	v_pk_mul_f32 v[166:167], v[106:107], v[150:151]
	v_mul_f32_e32 v150, 0xbfb8aa3b, v98
	v_mul_f32_e32 v151, 0xbfb8aa3b, v99
	v_exp_f32_e32 v150, v150
	v_exp_f32_e32 v151, v151
	v_add_f32_e32 v148, 1.0, v148
	v_add_f32_e32 v149, 1.0, v149
	v_rcp_f32_e32 v148, v148
	v_rcp_f32_e32 v149, v149
	v_add_f32_e32 v150, 1.0, v150
	v_add_f32_e32 v151, 1.0, v151
	v_rcp_f32_e32 v150, v150
	v_rcp_f32_e32 v151, v151
	v_pk_mul_f32 v[168:169], v[96:97], v[148:149]
	v_lshlrev_b64 v[148:149], 11, v[172:173]
	v_lshl_add_u64 v[148:149], s[50:51], 0, v[148:149]
	v_lshl_add_u64 v[148:149], v[148:149], 0, v[160:161]
	v_pk_mul_f32 v[170:171], v[98:99], v[150:151]
	s_waitcnt vmcnt(5)
	v_mov_b32_e32 v148, v192
	v_mov_b32_e32 v149, v193
	v_mov_b32_e32 v150, v194
	v_mov_b32_e32 v151, v195
	v_add_u32_e32 v187, 0x8000, v187
	global_load_dwordx4 v[192:195], v187, s[50:51] sc1
	v_mov_b32_e32 v174, v211
	v_mov_b32_e32 v175, v211
	v_mov_b32_e32 v176, v211
	v_mov_b32_e32 v177, v211
	v_mov_b32_e32 v178, v211
	v_mov_b32_e32 v180, v211
	v_pk_mul_f32 v[166:167], v[110:111], v[166:167]
	v_pk_mul_f32 v[170:171], v[102:103], v[170:171]
	v_cndmask_b32_e64 v163, v148, v144, s[4:5]
	v_cndmask_b32_e64 v144, v144, v148, s[0:1]
	s_nop 0
	v_mov_b32_dpp v174, v163 row_ror:1 row_mask:0xf bank_mask:0xf
	v_mov_b32_e32 v163, v211
	s_nop 1
	v_mov_b32_dpp v163, v144 row_ror:2 row_mask:0xf bank_mask:0xf
	v_cndmask_b32_e64 v144, v149, v145, s[4:5]
	v_cndmask_b32_e64 v145, v145, v149, s[0:1]
	s_nop 0
	v_mov_b32_dpp v175, v144 row_ror:1 row_mask:0xf bank_mask:0xf
	v_mov_b32_dpp v176, v145 row_ror:2 row_mask:0xf bank_mask:0xf
	v_cndmask_b32_e64 v144, v150, v146, s[4:5]
	v_cndmask_b32_e64 v145, v146, v150, s[0:1]
	s_nop 0
	v_mov_b32_dpp v177, v144 row_ror:1 row_mask:0xf bank_mask:0xf
	v_mov_b32_dpp v178, v145 row_ror:2 row_mask:0xf bank_mask:0xf
	v_cndmask_b32_e64 v144, v151, v147, s[4:5]
	v_cndmask_b32_e64 v145, v147, v151, s[0:1]
	v_pk_mul_f32 v[146:147], v[100:101], v[168:169]
	v_mov_b32_dpp v179, v144 row_ror:1 row_mask:0xf bank_mask:0xf
	v_mov_b32_dpp v180, v145 row_ror:2 row_mask:0xf bank_mask:0xf
	v_lshlrev_b32_e32 v145, 16, v174
	v_lshlrev_b32_e32 v144, 16, v148
	v_lshlrev_b32_e32 v168, 16, v163
	v_pk_mul_f32 v[144:145], v[156:157], v[144:145]
	v_and_b32_e32 v163, 0xffff0000, v163
	v_fma_f32 v145, v136, v168, v145
	v_add_f32_e32 v168, v144, v145
	v_and_b32_e32 v145, 0xffff0000, v174
	v_and_b32_e32 v144, 0xffff0000, v148
	v_pk_mul_f32 v[144:145], v[140:141], v[144:145]
	v_lshlrev_b32_e32 v169, 16, v176
	v_fma_f32 v145, v137, v163, v145
	v_add_f32_e32 v163, v144, v145
	v_lshlrev_b32_e32 v145, 16, v175
	v_lshlrev_b32_e32 v144, 16, v149
	v_pk_mul_f32 v[144:145], v[152:153], v[144:145]
	v_and_b32_e32 v174, 0xffff0000, v176
	v_fma_f32 v145, v138, v169, v145
	v_add_f32_e32 v169, v144, v145
	v_and_b32_e32 v145, 0xffff0000, v175
	v_and_b32_e32 v144, 0xffff0000, v149
	v_pk_mul_f32 v[144:145], v[142:143], v[144:145]
	v_lshlrev_b32_e32 v175, 16, v178
	v_fma_f32 v145, v139, v174, v145
	v_add_f32_e32 v174, v144, v145
	v_lshlrev_b32_e32 v145, 16, v177
	v_lshlrev_b32_e32 v144, 16, v150
	v_pk_mul_f32 v[144:145], v[154:155], v[144:145]
	v_and_b32_e32 v176, 0xffff0000, v178
	v_fma_f32 v145, v112, v175, v145
	v_add_f32_e32 v175, v144, v145
	v_and_b32_e32 v145, 0xffff0000, v177
	v_and_b32_e32 v144, 0xffff0000, v150
	v_pk_mul_f32 v[144:145], v[116:117], v[144:145]
	v_lshlrev_b32_e32 v177, 16, v180
	v_fma_f32 v145, v113, v176, v145
	v_add_f32_e32 v176, v144, v145
	v_lshlrev_b32_e32 v145, 16, v179
	v_lshlrev_b32_e32 v144, 16, v151
	v_pk_mul_f32 v[144:145], v[158:159], v[144:145]
	v_and_b32_e32 v178, 0xffff0000, v180
	v_fma_f32 v145, v114, v177, v145
	v_add_f32_e32 v177, v144, v145
	v_and_b32_e32 v145, 0xffff0000, v179
	v_and_b32_e32 v144, 0xffff0000, v151
	v_pk_mul_f32 v[144:145], v[118:119], v[144:145]
	v_mul_f32_e32 v146, v146, v175
	v_fma_f32 v145, v115, v178, v145
	v_add_f32_e32 v178, v144, v145
	v_pk_mul_f32 v[144:145], v[108:109], v[164:165]
	v_lshlrev_b64 v[164:165], 12, v[172:173]
	v_mul_f32_e32 v144, v144, v168
	v_mul_f32_e32 v145, v145, v163
	v_cvt_pk_bf16_f32 v144, v144, v145
	v_mul_f32_e32 v145, v166, v169
	v_mul_f32_e32 v147, v147, v176
	v_lshl_add_u64 v[164:165], s[12:13], 0, v[164:165]
	v_mul_f32_e32 v163, v167, v174
	v_cvt_pk_bf16_f32 v145, v145, v163
	v_cvt_pk_bf16_f32 v146, v146, v147
	v_mul_f32_e32 v147, v170, v177
	v_lshl_add_u64 v[164:165], v[164:165], 0, v[160:161]
	v_mul_f32_e32 v163, v171, v178
	v_cvt_pk_bf16_f32 v147, v147, v163
	global_store_dwordx4 v[164:165], v[144:147], off offset:2048 sc1
	v_or_b32_e32 v172, 32, v162
	v_ashrrev_i32_e32 v173, 31, v172
	v_mul_f32_e32 v144, 0xbfb8aa3b, v88
	v_mul_f32_e32 v145, 0xbfb8aa3b, v89
	v_exp_f32_e32 v144, v144
	v_exp_f32_e32 v145, v145
	v_mul_f32_e32 v146, 0xbfb8aa3b, v90
	v_mul_f32_e32 v147, 0xbfb8aa3b, v91
	v_exp_f32_e32 v146, v146
	v_exp_f32_e32 v147, v147
	v_add_f32_e32 v144, 1.0, v144
	v_add_f32_e32 v145, 1.0, v145
	v_rcp_f32_e32 v144, v144
	v_rcp_f32_e32 v145, v145
	v_add_f32_e32 v146, 1.0, v146
	v_add_f32_e32 v147, 1.0, v147
	v_rcp_f32_e32 v146, v146
	v_rcp_f32_e32 v147, v147
	v_pk_mul_f32 v[164:165], v[88:89], v[144:145]
	v_mul_f32_e32 v144, 0xbfb8aa3b, v80
	v_mul_f32_e32 v145, 0xbfb8aa3b, v81
	v_exp_f32_e32 v144, v144
	v_exp_f32_e32 v145, v145
	v_pk_mul_f32 v[166:167], v[90:91], v[146:147]
	v_mul_f32_e32 v146, 0xbfb8aa3b, v82
	v_mul_f32_e32 v147, 0xbfb8aa3b, v83
	v_exp_f32_e32 v146, v146
	v_exp_f32_e32 v147, v147
	v_add_f32_e32 v144, 1.0, v144
	v_add_f32_e32 v145, 1.0, v145
	v_rcp_f32_e32 v144, v144
	v_rcp_f32_e32 v145, v145
	v_add_f32_e32 v146, 1.0, v146
	v_add_f32_e32 v147, 1.0, v147
	v_rcp_f32_e32 v146, v146
	v_rcp_f32_e32 v147, v147
	v_pk_mul_f32 v[168:169], v[80:81], v[144:145]
	v_lshlrev_b64 v[144:145], 11, v[172:173]
	v_lshl_add_u64 v[144:145], s[50:51], 0, v[144:145]
	v_lshl_add_u64 v[144:145], v[144:145], 0, v[160:161]
	v_pk_mul_f32 v[170:171], v[82:83], v[146:147]
	s_waitcnt vmcnt(6)
	v_mov_b32_e32 v144, v196
	v_mov_b32_e32 v145, v197
	v_mov_b32_e32 v146, v198
	v_mov_b32_e32 v147, v199
	v_add_u32_e32 v187, 0x8000, v187
	global_load_dwordx4 v[196:199], v187, s[50:51] sc1
	v_mov_b32_e32 v174, v211
	v_mov_b32_e32 v175, v211
	v_mov_b32_e32 v176, v211
	v_mov_b32_e32 v177, v211
	v_mov_b32_e32 v178, v211
	v_mov_b32_e32 v179, v211
	v_mov_b32_e32 v180, v211
	v_pk_mul_f32 v[166:167], v[94:95], v[166:167]
	v_pk_mul_f32 v[170:171], v[86:87], v[170:171]
	v_cndmask_b32_e64 v163, v144, v148, s[4:5]
	v_cndmask_b32_e64 v148, v148, v144, s[0:1]
	s_nop 0
	v_mov_b32_dpp v174, v163 row_ror:1 row_mask:0xf bank_mask:0xf
	v_mov_b32_e32 v163, v211
	s_nop 1
	v_mov_b32_dpp v163, v148 row_ror:2 row_mask:0xf bank_mask:0xf
	v_cndmask_b32_e64 v148, v145, v149, s[4:5]
	v_cndmask_b32_e64 v149, v149, v145, s[0:1]
	s_nop 0
	v_mov_b32_dpp v175, v148 row_ror:1 row_mask:0xf bank_mask:0xf
	v_mov_b32_dpp v176, v149 row_ror:2 row_mask:0xf bank_mask:0xf
	v_cndmask_b32_e64 v148, v146, v150, s[4:5]
	v_cndmask_b32_e64 v149, v150, v146, s[0:1]
	s_nop 0
	v_mov_b32_dpp v177, v148 row_ror:1 row_mask:0xf bank_mask:0xf
	v_mov_b32_dpp v178, v149 row_ror:2 row_mask:0xf bank_mask:0xf
	v_cndmask_b32_e64 v148, v147, v151, s[4:5]
	v_cndmask_b32_e64 v149, v151, v147, s[0:1]
	v_pk_mul_f32 v[150:151], v[84:85], v[168:169]
	v_mov_b32_dpp v179, v148 row_ror:1 row_mask:0xf bank_mask:0xf
	v_mov_b32_dpp v180, v149 row_ror:2 row_mask:0xf bank_mask:0xf
	v_lshlrev_b32_e32 v149, 16, v174
	v_lshlrev_b32_e32 v148, 16, v144
	v_lshlrev_b32_e32 v168, 16, v163
	v_pk_mul_f32 v[148:149], v[156:157], v[148:149]
	v_and_b32_e32 v163, 0xffff0000, v163
	v_fma_f32 v149, v136, v168, v149
	v_add_f32_e32 v168, v148, v149
	v_and_b32_e32 v149, 0xffff0000, v174
	v_and_b32_e32 v148, 0xffff0000, v144
	v_pk_mul_f32 v[148:149], v[140:141], v[148:149]
	v_lshlrev_b32_e32 v169, 16, v176
	v_fma_f32 v149, v137, v163, v149
	v_add_f32_e32 v163, v148, v149
	v_lshlrev_b32_e32 v149, 16, v175
	v_lshlrev_b32_e32 v148, 16, v145
	v_pk_mul_f32 v[148:149], v[152:153], v[148:149]
	v_and_b32_e32 v174, 0xffff0000, v176
	v_fma_f32 v149, v138, v169, v149
	v_add_f32_e32 v169, v148, v149
	v_and_b32_e32 v149, 0xffff0000, v175
	v_and_b32_e32 v148, 0xffff0000, v145
	v_pk_mul_f32 v[148:149], v[142:143], v[148:149]
	v_lshlrev_b32_e32 v175, 16, v178
	v_fma_f32 v149, v139, v174, v149
	v_add_f32_e32 v174, v148, v149
	v_lshlrev_b32_e32 v149, 16, v177
	v_lshlrev_b32_e32 v148, 16, v146
	v_pk_mul_f32 v[148:149], v[154:155], v[148:149]
	v_and_b32_e32 v176, 0xffff0000, v178
	v_fma_f32 v149, v112, v175, v149
	v_add_f32_e32 v175, v148, v149
	v_and_b32_e32 v149, 0xffff0000, v177
	v_and_b32_e32 v148, 0xffff0000, v146
	v_pk_mul_f32 v[148:149], v[116:117], v[148:149]
	v_lshlrev_b32_e32 v177, 16, v180
	v_fma_f32 v149, v113, v176, v149
	v_add_f32_e32 v176, v148, v149
	v_lshlrev_b32_e32 v149, 16, v179
	v_lshlrev_b32_e32 v148, 16, v147
	v_pk_mul_f32 v[148:149], v[158:159], v[148:149]
	v_and_b32_e32 v178, 0xffff0000, v180
	v_fma_f32 v149, v114, v177, v149
	v_add_f32_e32 v177, v148, v149
	v_and_b32_e32 v149, 0xffff0000, v179
	v_and_b32_e32 v148, 0xffff0000, v147
	v_pk_mul_f32 v[148:149], v[118:119], v[148:149]
	v_mul_f32_e32 v150, v150, v175
	v_fma_f32 v149, v115, v178, v149
	v_add_f32_e32 v178, v148, v149
	v_pk_mul_f32 v[148:149], v[92:93], v[164:165]
	v_mul_f32_e32 v151, v151, v176
	v_mul_f32_e32 v148, v148, v168
	v_mul_f32_e32 v149, v149, v163
	v_or_b32_e32 v168, 48, v162
	v_cvt_pk_bf16_f32 v148, v148, v149
	v_mul_f32_e32 v149, v166, v169
	v_mul_f32_e32 v163, v167, v174
	v_lshlrev_b64 v[164:165], 12, v[172:173]
	v_ashrrev_i32_e32 v169, 31, v168
	v_cvt_pk_bf16_f32 v149, v149, v163
	v_cvt_pk_bf16_f32 v150, v150, v151
	v_mul_f32_e32 v151, v170, v177
	v_mul_f32_e32 v163, v171, v178
	v_lshl_add_u64 v[164:165], s[12:13], 0, v[164:165]
	v_lshlrev_b64 v[170:171], 11, v[168:169]
	v_lshl_add_u64 v[164:165], v[164:165], 0, v[160:161]
	v_lshl_add_u64 v[170:171], s[50:51], 0, v[170:171]
	v_cvt_pk_bf16_f32 v151, v151, v163
	global_store_dwordx4 v[164:165], v[148:151], off offset:2048 sc1
	v_lshl_add_u64 v[170:171], v[170:171], 0, v[160:161]
	s_waitcnt vmcnt(7)
	v_mov_b32_e32 v176, v228
	v_mov_b32_e32 v177, v229
	v_mov_b32_e32 v178, v230
	v_mov_b32_e32 v179, v231
	v_mul_f32_e32 v148, 0xbfb8aa3b, v72
	v_mul_f32_e32 v149, 0xbfb8aa3b, v73
	v_exp_f32_e32 v148, v148
	v_exp_f32_e32 v149, v149
	v_mul_f32_e32 v150, 0xbfb8aa3b, v74
	v_mul_f32_e32 v151, 0xbfb8aa3b, v75
	v_add_f32_e32 v148, 1.0, v148
	v_add_f32_e32 v149, 1.0, v149
	v_rcp_f32_e32 v148, v148
	v_rcp_f32_e32 v149, v149
	v_exp_f32_e32 v150, v150
	v_exp_f32_e32 v151, v151
	v_mov_b32_e32 v170, v211
	v_pk_mul_f32 v[164:165], v[72:73], v[148:149]
	v_mul_f32_e32 v148, 0xbfb8aa3b, v64
	v_mul_f32_e32 v149, 0xbfb8aa3b, v65
	v_exp_f32_e32 v148, v148
	v_exp_f32_e32 v149, v149
	v_add_f32_e32 v150, 1.0, v150
	v_add_f32_e32 v151, 1.0, v151
	v_add_f32_e32 v148, 1.0, v148
	v_add_f32_e32 v149, 1.0, v149
	v_rcp_f32_e32 v148, v148
	v_rcp_f32_e32 v149, v149
	v_rcp_f32_e32 v150, v150
	v_rcp_f32_e32 v151, v151
	v_mov_b32_e32 v172, v211
	v_mov_b32_e32 v173, v211
	v_mov_b32_e32 v174, v211
	v_mov_b32_e32 v175, v211
	v_pk_mul_f32 v[148:149], v[64:65], v[148:149]
	v_pk_mul_f32 v[166:167], v[74:75], v[150:151]
	v_mul_f32_e32 v150, 0xbfb8aa3b, v66
	v_mul_f32_e32 v151, 0xbfb8aa3b, v67
	v_pk_mul_f32 v[182:183], v[68:69], v[148:149]
	v_exp_f32_e32 v150, v150
	v_exp_f32_e32 v151, v151
	v_pk_mul_f32 v[164:165], v[76:77], v[164:165]
	v_pk_mul_f32 v[166:167], v[78:79], v[166:167]
	v_add_f32_e32 v150, 1.0, v150
	v_add_f32_e32 v151, 1.0, v151
	v_rcp_f32_e32 v150, v150
	v_rcp_f32_e32 v151, v151
	v_cndmask_b32_e64 v163, v176, v144, s[4:5]
	v_cndmask_b32_e64 v144, v144, v176, s[0:1]
	s_nop 0
	v_mov_b32_dpp v170, v163 row_ror:1 row_mask:0xf bank_mask:0xf
	v_mov_b32_e32 v163, v211
	v_and_b32_e32 v171, 0xffff0000, v170
	v_pk_mul_f32 v[150:151], v[66:67], v[150:151]
	v_mov_b32_dpp v163, v144 row_ror:2 row_mask:0xf bank_mask:0xf
	v_cndmask_b32_e64 v144, v177, v145, s[4:5]
	v_cndmask_b32_e64 v145, v145, v177, s[0:1]
	v_lshlrev_b32_e32 v148, 16, v163
	v_mov_b32_dpp v172, v144 row_ror:1 row_mask:0xf bank_mask:0xf
	v_mov_b32_dpp v173, v145 row_ror:2 row_mask:0xf bank_mask:0xf
	v_cndmask_b32_e64 v144, v178, v146, s[4:5]
	v_cndmask_b32_e64 v145, v146, v178, s[0:1]
	v_pk_mul_f32 v[180:181], v[70:71], v[150:151]
	v_mov_b32_dpp v174, v144 row_ror:1 row_mask:0xf bank_mask:0xf
	v_mov_b32_dpp v175, v145 row_ror:2 row_mask:0xf bank_mask:0xf
	v_cndmask_b32_e64 v144, v179, v147, s[4:5]
	v_cndmask_b32_e64 v145, v147, v179, s[0:1]
	s_nop 0
	v_mov_b32_dpp v184, v144 row_ror:1 row_mask:0xf bank_mask:0xf
	v_mov_b32_dpp v185, v145 row_ror:2 row_mask:0xf bank_mask:0xf
	v_lshlrev_b32_e32 v145, 16, v170
	v_lshlrev_b32_e32 v144, 16, v176
	v_pk_mul_f32 v[146:147], v[156:157], v[144:145]
	v_and_b32_e32 v170, 0xffff0000, v176
	v_fma_f32 v145, v136, v148, v147
	v_add_f32_e32 v186, v146, v145
	v_and_b32_e32 v145, 0xffff0000, v163
	v_pk_mul_f32 v[146:147], v[140:141], v[170:171]
	s_nop 0
	v_fma_f32 v145, v137, v145, v147
	v_add_f32_e32 v163, v146, v145
	v_lshlrev_b32_e32 v147, 16, v172
	v_lshlrev_b32_e32 v146, 16, v177
	v_lshlrev_b32_e32 v145, 16, v173
	v_pk_mul_f32 v[148:149], v[152:153], v[146:147]
	v_mul_f32_e32 v163, v165, v163
	v_fma_f32 v145, v138, v145, v149
	v_add_f32_e32 v147, v148, v145
	v_and_b32_e32 v145, 0xffff0000, v173
	v_and_b32_e32 v173, 0xffff0000, v172
	v_and_b32_e32 v172, 0xffff0000, v177
	v_pk_mul_f32 v[148:149], v[142:143], v[172:173]
	v_mul_f32_e32 v147, v166, v147
	v_fma_f32 v145, v139, v145, v149
	v_add_f32_e32 v171, v148, v145
	v_lshlrev_b32_e32 v149, 16, v174
	v_lshlrev_b32_e32 v148, 16, v178
	v_lshlrev_b32_e32 v145, 16, v175
	v_pk_mul_f32 v[150:151], v[154:155], v[148:149]
	s_nop 0
	v_fma_f32 v145, v112, v145, v151
	v_add_f32_e32 v149, v150, v145
	v_and_b32_e32 v145, 0xffff0000, v175
	v_and_b32_e32 v175, 0xffff0000, v174
	v_and_b32_e32 v174, 0xffff0000, v178
	v_pk_mul_f32 v[150:151], v[116:117], v[174:175]
	s_nop 0
	v_fma_f32 v145, v113, v145, v151
	v_add_f32_e32 v173, v150, v145
	v_lshlrev_b32_e32 v151, 16, v184
	v_lshlrev_b32_e32 v150, 16, v179
	v_lshlrev_b32_e32 v145, 16, v185
	v_pk_mul_f32 v[176:177], v[158:159], v[150:151]
	s_nop 0
	v_fma_f32 v145, v114, v145, v177
	v_add_f32_e32 v151, v176, v145
	v_and_b32_e32 v177, 0xffff0000, v184
	v_and_b32_e32 v176, 0xffff0000, v179
	v_and_b32_e32 v145, 0xffff0000, v185
	v_pk_mul_f32 v[178:179], v[118:119], v[176:177]
	s_nop 0
	v_fma_f32 v145, v115, v145, v179
	v_add_f32_e32 v175, v178, v145
	v_bitop3_b32 v145, v162, s16, 48 bitop3:0xc8
	v_mul_f32_e32 v162, v164, v186
	v_cvt_pk_bf16_f32 v162, v162, v163
	v_mul_f32_e32 v163, v167, v171
	v_lshlrev_b64 v[166:167], 12, v[168:169]
	v_lshl_add_u64 v[166:167], s[12:13], 0, v[166:167]
	s_movk_i32 s16, 0x7fd
	v_cvt_pk_bf16_f32 v163, v147, v163
	v_mul_f32_e32 v147, v182, v149
	v_mul_f32_e32 v149, v183, v173
	v_lshl_add_u64 v[166:167], v[166:167], 0, v[160:161]
	v_cmp_lt_u32_e32 vcc, s16, v145
	v_cvt_pk_bf16_f32 v164, v147, v149
	v_mul_f32_e32 v147, v180, v151
	v_mul_f32_e32 v149, v181, v175
	v_cvt_pk_bf16_f32 v165, v147, v149
	global_store_dwordx4 v[166:167], v[162:165], off offset:2048 sc1
	s_and_saveexec_b64 s[40:41], vcc
	s_cbranch_execz .LBB0_316
	v_lshrrev_b32_e32 v147, 21, v169
	v_add_u32_e32 v147, v168, v147
	v_ashrrev_i32_e32 v162, 11, v147
	v_ashrrev_i32_e32 v163, 31, v162
	v_add_u32_e32 v164, 0xfffff802, v145
	v_mov_b32_e32 v165, v211
	v_lshlrev_b64 v[162:163], 13, v[162:163]
	v_lshl_add_u64 v[162:163], s[18:19], 0, v[162:163]
	v_lshlrev_b64 v[164:165], 12, v[164:165]
	v_lshl_add_u64 v[162:163], v[162:163], 0, v[164:165]
	v_lshl_add_u64 v[162:163], v[210:211], 2, v[162:163]
	v_mov_b32_e32 v145, v170
	v_mov_b32_e32 v147, v172
	v_mov_b32_e32 v149, v174
	v_mov_b32_e32 v151, v176
	global_store_dwordx4 v[162:163], v[144:147], off
	global_store_dwordx4 v[162:163], v[148:151], off offset:16
